# attention: score tiles accumulate onto -rowmax blocks (no per-element subtract in the softmax stream); rare rescale subtracts the shift from the tile
# baseline (speedup 1.0000x reference)
.LBB0_346:
	s_cmp_lg_u32 s1, 64
	s_cselect_b64 s[28:29], -1, 0
	s_and_b32 s4, 1, s1
	s_cselect_b32 s5, 0, 0x5800
	v_add3_u32 v235, s5, v223, v198
	v_add_u32_e32 v218, s5, v224
	ds_read_b128 v[236:239], v235
	ds_read_b128 v[240:243], v235 offset:6656
	ds_read_b128 v[244:247], v235 offset:32
	ds_read_b128 v[248:251], v235 offset:6688
	v_sub_f32_e32 v176, 0, v233
	v_sub_f32_e32 v177, 0, v233
	v_sub_f32_e32 v178, 0, v233
	v_sub_f32_e32 v179, 0, v233
	v_sub_f32_e32 v180, 0, v233
	v_sub_f32_e32 v181, 0, v233
	v_sub_f32_e32 v182, 0, v233
	v_sub_f32_e32 v183, 0, v233
	v_sub_f32_e32 v184, 0, v233
	v_sub_f32_e32 v185, 0, v233
	v_sub_f32_e32 v186, 0, v233
	v_sub_f32_e32 v187, 0, v233
	v_sub_f32_e32 v188, 0, v233
	v_sub_f32_e32 v189, 0, v233
	v_sub_f32_e32 v190, 0, v233
	v_sub_f32_e32 v191, 0, v233
	v_sub_f32_e32 v80, 0, v234
	v_sub_f32_e32 v81, 0, v234
	v_sub_f32_e32 v82, 0, v234
	v_sub_f32_e32 v83, 0, v234
	v_sub_f32_e32 v84, 0, v234
	v_sub_f32_e32 v85, 0, v234
	v_sub_f32_e32 v86, 0, v234
	v_sub_f32_e32 v87, 0, v234
	v_sub_f32_e32 v88, 0, v234
	v_sub_f32_e32 v89, 0, v234
	v_sub_f32_e32 v90, 0, v234
	v_sub_f32_e32 v91, 0, v234
	v_sub_f32_e32 v92, 0, v234
	v_sub_f32_e32 v93, 0, v234
	v_sub_f32_e32 v94, 0, v234
	v_sub_f32_e32 v95, 0, v234
	s_waitcnt lgkmcnt(3)
	v_mfma_f32_32x32x16_bf16 v[64:79], v[236:239], v[128:131], v[176:191]
	v_mfma_f32_32x32x16_bf16 v[96:111], v[236:239], v[152:155], v[80:95]
	ds_read_b128 v[236:239], v235 offset:64
	s_waitcnt lgkmcnt(3)
	v_mfma_f32_32x32x16_bf16 v[112:127], v[240:243], v[152:155], v[80:95]
	v_mfma_f32_32x32x16_bf16 v[80:95], v[240:243], v[128:131], v[176:191]
	ds_read_b128 v[240:243], v235 offset:6720
	s_waitcnt lgkmcnt(3)
	v_mfma_f32_32x32x16_bf16 v[64:79], v[244:247], v[132:135], v[64:79]
	v_mfma_f32_32x32x16_bf16 v[96:111], v[244:247], v[156:159], v[96:111]
	ds_read_b128 v[244:247], v235 offset:96
	s_waitcnt lgkmcnt(3)
	v_mfma_f32_32x32x16_bf16 v[80:95], v[248:251], v[132:135], v[80:95]
	v_mfma_f32_32x32x16_bf16 v[112:127], v[248:251], v[156:159], v[112:127]
	ds_read_b128 v[248:251], v235 offset:6752
	s_cmp_lg_u32 s1, 64
	s_cbranch_scc0 .Lat_skipld
	v_lshl_add_u64 v[214:215], s[88:89], 0, v[208:209]
	v_lshl_add_u64 v[216:217], s[88:89], 0, v[210:211]
	global_load_dwordx4 v[176:179], v[214:215], off
	global_load_dwordx4 v[180:183], v[216:217], off
	v_lshl_add_u64 v[214:215], s[88:89], 0, v[212:213]
	v_lshl_add_u64 v[216:217], s[88:89], 0, v[204:205]
	global_load_dwordx4 v[184:187], v[214:215], off
	global_load_dwordx4 v[188:191], v[216:217], off
	v_lshl_add_u64 v[214:215], s[88:89], 0, v[206:207]
	global_load_dwordx4 v[192:195], v[214:215], off
.Lat_skipld:
	s_waitcnt lgkmcnt(3)
	v_mfma_f32_32x32x16_bf16 v[64:79], v[236:239], v[136:139], v[64:79]
	v_mfma_f32_32x32x16_bf16 v[96:111], v[236:239], v[160:163], v[96:111]
	ds_read_b128 v[236:239], v235 offset:128
	s_waitcnt lgkmcnt(3)
	v_mfma_f32_32x32x16_bf16 v[80:95], v[240:243], v[136:139], v[80:95]
	v_mfma_f32_32x32x16_bf16 v[112:127], v[240:243], v[160:163], v[112:127]
	ds_read_b128 v[240:243], v235 offset:6784
	s_waitcnt lgkmcnt(3)
	v_mfma_f32_32x32x16_bf16 v[64:79], v[244:247], v[140:143], v[64:79]
	v_mfma_f32_32x32x16_bf16 v[96:111], v[244:247], v[164:167], v[96:111]
	ds_read_b128 v[244:247], v235 offset:160
	s_waitcnt lgkmcnt(3)
	v_mfma_f32_32x32x16_bf16 v[80:95], v[248:251], v[140:143], v[80:95]
	v_mfma_f32_32x32x16_bf16 v[112:127], v[248:251], v[164:167], v[112:127]
	ds_read_b128 v[248:251], v235 offset:6816
	s_waitcnt lgkmcnt(3)
	v_mfma_f32_32x32x16_bf16 v[64:79], v[236:239], v[144:147], v[64:79]
	v_mfma_f32_32x32x16_bf16 v[96:111], v[236:239], v[168:171], v[96:111]
	ds_read_b128 v[236:239], v218 offset:13312
	s_waitcnt lgkmcnt(3)
	v_mfma_f32_32x32x16_bf16 v[80:95], v[240:243], v[144:147], v[80:95]
	v_mfma_f32_32x32x16_bf16 v[112:127], v[240:243], v[168:171], v[112:127]
	ds_read_b128 v[240:243], v218 offset:17920
	s_waitcnt lgkmcnt(3)
	v_mfma_f32_32x32x16_bf16 v[64:79], v[244:247], v[148:151], v[64:79]
	v_mfma_f32_32x32x16_bf16 v[96:111], v[244:247], v[172:175], v[96:111]
	s_waitcnt lgkmcnt(2)
	v_mfma_f32_32x32x16_bf16 v[80:95], v[248:251], v[148:151], v[80:95]
	v_mfma_f32_32x32x16_bf16 v[112:127], v[248:251], v[172:175], v[112:127]
	ds_read_b128 v[244:247], v218 offset:13344
	ds_read_b128 v[248:251], v218 offset:17952
	s_nop 7
	s_nop 1
	v_max3_f32 v214, v64, v65, v66
	v_max3_f32 v215, v80, v81, v82
	v_max3_f32 v216, v96, v97, v98
	v_max3_f32 v217, v112, v113, v114
	v_max3_f32 v214, v214, v67, v68
	v_max3_f32 v215, v215, v83, v84
	v_max3_f32 v216, v216, v99, v100
	v_max3_f32 v217, v217, v115, v116
	v_max3_f32 v214, v214, v69, v70
	v_max3_f32 v215, v215, v85, v86
	v_max3_f32 v216, v216, v101, v102
	v_max3_f32 v217, v217, v117, v118
	v_max3_f32 v214, v214, v71, v72
	v_max3_f32 v215, v215, v87, v88
	v_max3_f32 v216, v216, v103, v104
	v_max3_f32 v217, v217, v119, v120
	v_max3_f32 v214, v214, v73, v74
	v_max3_f32 v215, v215, v89, v90
	v_max3_f32 v216, v216, v105, v106
	v_max3_f32 v217, v217, v121, v122
	v_max3_f32 v214, v214, v75, v76
	v_max3_f32 v215, v215, v91, v92
	v_max3_f32 v216, v216, v107, v108
	v_max3_f32 v217, v217, v123, v124
	v_max3_f32 v214, v214, v77, v78
	v_max3_f32 v215, v215, v93, v94
	v_max3_f32 v216, v216, v109, v110
	v_max3_f32 v217, v217, v125, v126
	v_max_f32_e32 v214, v214, v79
	v_max_f32_e32 v215, v215, v95
	v_max_f32_e32 v216, v216, v111
	v_max_f32_e32 v217, v217, v127
	v_max_f32_e32 v214, v214, v215
	v_max_f32_e32 v216, v216, v217
	ds_bpermute_b32 v215, v201, v214
	ds_bpermute_b32 v217, v201, v216
	s_waitcnt lgkmcnt(0)
	v_max_f32_e32 v214, v214, v215
	v_max_f32_e32 v216, v216, v217
	v_cmp_lt_f32_e32 vcc, s56, v214
	s_cbranch_vccz .Lat_nr0
	v_max_f32_e32 v215, 0, v214
	v_sub_f32_e32 v196, 0, v215
	v_exp_f32_e32 v196, v196
	v_add_f32_e32 v233, v233, v215
	s_nop 0
	v_mul_f32_e32 v202, v196, v202
	v_mul_f32_e32 v0, v196, v0
	v_mul_f32_e32 v1, v196, v1
	v_mul_f32_e32 v2, v196, v2
	v_mul_f32_e32 v3, v196, v3
	v_mul_f32_e32 v4, v196, v4
	v_mul_f32_e32 v5, v196, v5
	v_mul_f32_e32 v6, v196, v6
	v_mul_f32_e32 v7, v196, v7
	v_mul_f32_e32 v8, v196, v8
	v_mul_f32_e32 v9, v196, v9
	v_mul_f32_e32 v10, v196, v10
	v_mul_f32_e32 v11, v196, v11
	v_mul_f32_e32 v12, v196, v12
	v_mul_f32_e32 v13, v196, v13
	v_mul_f32_e32 v14, v196, v14
	v_mul_f32_e32 v15, v196, v15
	v_mul_f32_e32 v16, v196, v16
	v_mul_f32_e32 v17, v196, v17
	v_mul_f32_e32 v18, v196, v18
	v_mul_f32_e32 v19, v196, v19
	v_mul_f32_e32 v20, v196, v20
	v_mul_f32_e32 v21, v196, v21
	v_mul_f32_e32 v22, v196, v22
	v_mul_f32_e32 v23, v196, v23
	v_mul_f32_e32 v24, v196, v24
	v_mul_f32_e32 v25, v196, v25
	v_mul_f32_e32 v26, v196, v26
	v_mul_f32_e32 v27, v196, v27
	v_mul_f32_e32 v28, v196, v28
	v_mul_f32_e32 v29, v196, v29
	v_mul_f32_e32 v30, v196, v30
	v_mul_f32_e32 v31, v196, v31
	v_sub_f32_e32 v64, v64, v215
	v_sub_f32_e32 v65, v65, v215
	v_sub_f32_e32 v66, v66, v215
	v_sub_f32_e32 v67, v67, v215
	v_sub_f32_e32 v68, v68, v215
	v_sub_f32_e32 v69, v69, v215
	v_sub_f32_e32 v70, v70, v215
	v_sub_f32_e32 v71, v71, v215
	v_sub_f32_e32 v72, v72, v215
	v_sub_f32_e32 v73, v73, v215
	v_sub_f32_e32 v74, v74, v215
	v_sub_f32_e32 v75, v75, v215
	v_sub_f32_e32 v76, v76, v215
	v_sub_f32_e32 v77, v77, v215
	v_sub_f32_e32 v78, v78, v215
	v_sub_f32_e32 v79, v79, v215
	v_sub_f32_e32 v80, v80, v215
	v_sub_f32_e32 v81, v81, v215
	v_sub_f32_e32 v82, v82, v215
	v_sub_f32_e32 v83, v83, v215
	v_sub_f32_e32 v84, v84, v215
	v_sub_f32_e32 v85, v85, v215
	v_sub_f32_e32 v86, v86, v215
	v_sub_f32_e32 v87, v87, v215
	v_sub_f32_e32 v88, v88, v215
	v_sub_f32_e32 v89, v89, v215
	v_sub_f32_e32 v90, v90, v215
	v_sub_f32_e32 v91, v91, v215
	v_sub_f32_e32 v92, v92, v215
	v_sub_f32_e32 v93, v93, v215
	v_sub_f32_e32 v94, v94, v215
	v_sub_f32_e32 v95, v95, v215
.Lat_nr0:
	v_cmp_lt_f32_e32 vcc, s56, v216
	s_cbranch_vccz .Lat_nr1
	v_max_f32_e32 v217, 0, v216
	v_sub_f32_e32 v196, 0, v217
	v_exp_f32_e32 v196, v196
	v_add_f32_e32 v234, v234, v217
	s_nop 0
	v_mul_f32_e32 v203, v196, v203
	v_mul_f32_e32 v32, v196, v32
	v_mul_f32_e32 v33, v196, v33
	v_mul_f32_e32 v34, v196, v34
	v_mul_f32_e32 v35, v196, v35
	v_mul_f32_e32 v36, v196, v36
	v_mul_f32_e32 v37, v196, v37
	v_mul_f32_e32 v38, v196, v38
	v_mul_f32_e32 v39, v196, v39
	v_mul_f32_e32 v40, v196, v40
	v_mul_f32_e32 v41, v196, v41
	v_mul_f32_e32 v42, v196, v42
	v_mul_f32_e32 v43, v196, v43
	v_mul_f32_e32 v44, v196, v44
	v_mul_f32_e32 v45, v196, v45
	v_mul_f32_e32 v46, v196, v46
	v_mul_f32_e32 v47, v196, v47
	v_mul_f32_e32 v48, v196, v48
	v_mul_f32_e32 v49, v196, v49
	v_mul_f32_e32 v50, v196, v50
	v_mul_f32_e32 v51, v196, v51
	v_mul_f32_e32 v52, v196, v52
	v_mul_f32_e32 v53, v196, v53
	v_mul_f32_e32 v54, v196, v54
	v_mul_f32_e32 v55, v196, v55
	v_mul_f32_e32 v56, v196, v56
	v_mul_f32_e32 v57, v196, v57
	v_mul_f32_e32 v58, v196, v58
	v_mul_f32_e32 v59, v196, v59
	v_mul_f32_e32 v60, v196, v60
	v_mul_f32_e32 v61, v196, v61
	v_mul_f32_e32 v62, v196, v62
	v_mul_f32_e32 v63, v196, v63
	v_sub_f32_e32 v96, v96, v217
	v_sub_f32_e32 v97, v97, v217
	v_sub_f32_e32 v98, v98, v217
	v_sub_f32_e32 v99, v99, v217
	v_sub_f32_e32 v100, v100, v217
	v_sub_f32_e32 v101, v101, v217
	v_sub_f32_e32 v102, v102, v217
	v_sub_f32_e32 v103, v103, v217
	v_sub_f32_e32 v104, v104, v217
	v_sub_f32_e32 v105, v105, v217
	v_sub_f32_e32 v106, v106, v217
	v_sub_f32_e32 v107, v107, v217
	v_sub_f32_e32 v108, v108, v217
	v_sub_f32_e32 v109, v109, v217
	v_sub_f32_e32 v110, v110, v217
	v_sub_f32_e32 v111, v111, v217
	v_sub_f32_e32 v112, v112, v217
	v_sub_f32_e32 v113, v113, v217
	v_sub_f32_e32 v114, v114, v217
	v_sub_f32_e32 v115, v115, v217
	v_sub_f32_e32 v116, v116, v217
	v_sub_f32_e32 v117, v117, v217
	v_sub_f32_e32 v118, v118, v217
	v_sub_f32_e32 v119, v119, v217
	v_sub_f32_e32 v120, v120, v217
	v_sub_f32_e32 v121, v121, v217
	v_sub_f32_e32 v122, v122, v217
	v_sub_f32_e32 v123, v123, v217
	v_sub_f32_e32 v124, v124, v217
	v_sub_f32_e32 v125, v125, v217
	v_sub_f32_e32 v126, v126, v217
	v_sub_f32_e32 v127, v127, v217
.Lat_nr1:
	v_exp_f32_e32 v64, v64
	v_exp_f32_e32 v65, v65
	v_exp_f32_e32 v66, v66
	v_exp_f32_e32 v67, v67
	v_add_f32_e32 v202, v202, v64
	v_exp_f32_e32 v68, v68
	v_exp_f32_e32 v69, v69
	v_add_f32_e32 v202, v202, v66
	v_exp_f32_e32 v70, v70
	v_add_f32_e32 v214, v65, v67
	v_cvt_pk_bf16_f32 v64, v64, v65
	v_exp_f32_e32 v71, v71
	v_add_f32_e32 v202, v202, v68
	v_exp_f32_e32 v72, v72
	v_add_f32_e32 v214, v214, v69
	v_cvt_pk_bf16_f32 v65, v66, v67
	v_exp_f32_e32 v73, v73
	v_add_f32_e32 v202, v202, v70
	v_exp_f32_e32 v74, v74
	v_add_f32_e32 v214, v214, v71
	v_cvt_pk_bf16_f32 v66, v68, v69
	v_exp_f32_e32 v75, v75
	v_add_f32_e32 v202, v202, v72
	v_exp_f32_e32 v76, v76
	v_add_f32_e32 v214, v214, v73
	v_cvt_pk_bf16_f32 v67, v70, v71
	v_exp_f32_e32 v77, v77
	v_add_f32_e32 v202, v202, v74
	v_mfma_f32_32x32x16_bf16 v[16:31], v[236:239], v[64:67], v[16:31]
	v_exp_f32_e32 v78, v78
	v_add_f32_e32 v214, v214, v75
	v_cvt_pk_bf16_f32 v68, v72, v73
	v_exp_f32_e32 v79, v79
	v_add_f32_e32 v202, v202, v76
	v_exp_f32_e32 v80, v80
	v_add_f32_e32 v214, v214, v77
	v_cvt_pk_bf16_f32 v69, v74, v75
	v_mfma_f32_32x32x16_bf16 v[0:15], v[240:243], v[64:67], v[0:15]
	v_exp_f32_e32 v81, v81
	v_add_f32_e32 v202, v202, v78
	v_exp_f32_e32 v82, v82
	v_add_f32_e32 v214, v214, v79
	v_cvt_pk_bf16_f32 v70, v76, v77
	v_exp_f32_e32 v83, v83
	v_add_f32_e32 v202, v202, v80
	v_exp_f32_e32 v84, v84
	v_add_f32_e32 v214, v214, v81
	v_cvt_pk_bf16_f32 v71, v78, v79
	v_exp_f32_e32 v85, v85
	v_add_f32_e32 v202, v202, v82
	v_mfma_f32_32x32x16_bf16 v[16:31], v[244:247], v[68:71], v[16:31]
	v_exp_f32_e32 v86, v86
	v_add_f32_e32 v214, v214, v83
	v_cvt_pk_bf16_f32 v72, v80, v81
	v_exp_f32_e32 v87, v87
	v_add_f32_e32 v202, v202, v84
	v_exp_f32_e32 v88, v88
	v_add_f32_e32 v214, v214, v85
	v_cvt_pk_bf16_f32 v73, v82, v83
	v_mfma_f32_32x32x16_bf16 v[0:15], v[248:251], v[68:71], v[0:15]
	v_exp_f32_e32 v89, v89
	v_add_f32_e32 v202, v202, v86
	v_exp_f32_e32 v90, v90
	v_add_f32_e32 v214, v214, v87
	v_cvt_pk_bf16_f32 v74, v84, v85
	v_exp_f32_e32 v91, v91
	v_add_f32_e32 v202, v202, v88
	v_exp_f32_e32 v92, v92
	v_add_f32_e32 v214, v214, v89
	v_cvt_pk_bf16_f32 v75, v86, v87
	v_exp_f32_e32 v93, v93
	v_add_f32_e32 v202, v202, v90
	v_exp_f32_e32 v94, v94
	v_add_f32_e32 v214, v214, v91
	v_cvt_pk_bf16_f32 v76, v88, v89
	v_exp_f32_e32 v95, v95
	v_add_f32_e32 v202, v202, v92
	v_add_f32_e32 v214, v214, v93
	v_cvt_pk_bf16_f32 v77, v90, v91
	v_add_f32_e32 v202, v202, v94
	v_add_f32_e32 v214, v214, v95
	v_cvt_pk_bf16_f32 v78, v92, v93
	v_cvt_pk_bf16_f32 v79, v94, v95
	v_add_f32_e32 v202, v202, v214
	ds_read_b128 v[80:83], v218 offset:13376
	ds_read_b128 v[84:87], v218 offset:17984
	ds_read_b128 v[88:91], v218 offset:13408
	ds_read_b128 v[92:95], v218 offset:18016
	v_exp_f32_e32 v96, v96
	v_exp_f32_e32 v97, v97
	v_exp_f32_e32 v98, v98
	v_exp_f32_e32 v99, v99
	v_add_f32_e32 v203, v203, v96
	v_exp_f32_e32 v100, v100
	v_exp_f32_e32 v101, v101
	v_add_f32_e32 v203, v203, v98
	v_exp_f32_e32 v102, v102
	v_add_f32_e32 v216, v97, v99
	v_cvt_pk_bf16_f32 v96, v96, v97
	v_exp_f32_e32 v103, v103
	v_add_f32_e32 v203, v203, v100
	v_exp_f32_e32 v104, v104
	s_waitcnt lgkmcnt(3)
	v_mfma_f32_32x32x16_bf16 v[16:31], v[80:83], v[72:75], v[16:31]
	v_add_f32_e32 v216, v216, v101
	v_cvt_pk_bf16_f32 v97, v98, v99
	v_exp_f32_e32 v105, v105
	v_add_f32_e32 v203, v203, v102
	v_exp_f32_e32 v106, v106
	v_add_f32_e32 v216, v216, v103
	v_cvt_pk_bf16_f32 v98, v100, v101
	v_exp_f32_e32 v107, v107
	s_waitcnt lgkmcnt(2)
	v_mfma_f32_32x32x16_bf16 v[0:15], v[84:87], v[72:75], v[0:15]
	v_add_f32_e32 v203, v203, v104
	v_exp_f32_e32 v108, v108
	v_add_f32_e32 v216, v216, v105
	v_cvt_pk_bf16_f32 v99, v102, v103
	v_exp_f32_e32 v109, v109
	v_add_f32_e32 v203, v203, v106
	v_exp_f32_e32 v110, v110
	v_add_f32_e32 v216, v216, v107
	s_waitcnt lgkmcnt(1)
	v_mfma_f32_32x32x16_bf16 v[16:31], v[88:91], v[76:79], v[16:31]
	v_cvt_pk_bf16_f32 v100, v104, v105
	v_exp_f32_e32 v111, v111
	v_add_f32_e32 v203, v203, v108
	v_exp_f32_e32 v112, v112
	v_add_f32_e32 v216, v216, v109
	v_cvt_pk_bf16_f32 v101, v106, v107
	v_exp_f32_e32 v113, v113
	v_add_f32_e32 v203, v203, v110
	s_waitcnt lgkmcnt(0)
	v_mfma_f32_32x32x16_bf16 v[0:15], v[92:95], v[76:79], v[0:15]
	v_exp_f32_e32 v114, v114
	v_add_f32_e32 v216, v216, v111
	v_cvt_pk_bf16_f32 v102, v108, v109
	v_exp_f32_e32 v115, v115
	v_add_f32_e32 v203, v203, v112
	v_exp_f32_e32 v116, v116
	v_add_f32_e32 v216, v216, v113
	v_cvt_pk_bf16_f32 v103, v110, v111
	v_mfma_f32_32x32x16_bf16 v[48:63], v[236:239], v[96:99], v[48:63]
	v_exp_f32_e32 v117, v117
	v_add_f32_e32 v203, v203, v114
	v_exp_f32_e32 v118, v118
	v_add_f32_e32 v216, v216, v115
	v_cvt_pk_bf16_f32 v104, v112, v113
	v_exp_f32_e32 v119, v119
	v_add_f32_e32 v203, v203, v116
	v_exp_f32_e32 v120, v120
	v_mfma_f32_32x32x16_bf16 v[32:47], v[240:243], v[96:99], v[32:47]
	v_add_f32_e32 v216, v216, v117
	v_cvt_pk_bf16_f32 v105, v114, v115
	v_exp_f32_e32 v121, v121
	v_add_f32_e32 v203, v203, v118
	v_exp_f32_e32 v122, v122
	v_add_f32_e32 v216, v216, v119
	v_cvt_pk_bf16_f32 v106, v116, v117
	v_exp_f32_e32 v123, v123
	v_mfma_f32_32x32x16_bf16 v[48:63], v[244:247], v[100:103], v[48:63]
	v_add_f32_e32 v203, v203, v120
	v_exp_f32_e32 v124, v124
	v_add_f32_e32 v216, v216, v121
	v_cvt_pk_bf16_f32 v107, v118, v119
	v_exp_f32_e32 v125, v125
	v_add_f32_e32 v203, v203, v122
	v_exp_f32_e32 v126, v126
	v_add_f32_e32 v216, v216, v123
	v_mfma_f32_32x32x16_bf16 v[32:47], v[248:251], v[100:103], v[32:47]
	v_cvt_pk_bf16_f32 v108, v120, v121
	v_exp_f32_e32 v127, v127
	v_add_f32_e32 v203, v203, v124
	v_add_f32_e32 v216, v216, v125
	v_cvt_pk_bf16_f32 v109, v122, v123
	v_add_f32_e32 v203, v203, v126
	v_add_f32_e32 v216, v216, v127
	v_cvt_pk_bf16_f32 v110, v124, v125
	v_cvt_pk_bf16_f32 v111, v126, v127
	v_add_f32_e32 v203, v203, v216
	s_nop 0
	v_mfma_f32_32x32x16_bf16 v[48:63], v[80:83], v[104:107], v[48:63]
	v_mfma_f32_32x32x16_bf16 v[32:47], v[84:87], v[104:107], v[32:47]
	s_cmp_eq_u32 s1, 64
	s_cbranch_scc1 .Lat_nowr
	s_cmp_eq_u32 s4, 1
	s_cselect_b32 s4, 0x5800, 0
	v_add3_u32 v214, s4, v225, v226
	v_add3_u32 v215, s4, v227, v228
	v_add3_u32 v216, s4, v229, v230
	v_add3_u32 v217, s4, v231, v200
	v_add3_u32 v196, s4, v232, v200
	s_waitcnt vmcnt(4)
	ds_write_b128 v214, v[176:179]
	s_waitcnt vmcnt(3)
	ds_write_b128 v215, v[180:183]
	s_waitcnt vmcnt(2)
	ds_write_b128 v216, v[184:187]
	s_waitcnt vmcnt(1)
	ds_write_b128 v217, v[188:191] offset:13312
	s_waitcnt vmcnt(0)
	ds_write_b128 v196, v[192:195] offset:13312
